# speedup vs baseline: 1.0144x; 1.0089x over previous
; __device__ __forceinline__ void finishSM(f32x16& p0, f32x16& p1, float alpha, float& l_reg, bf16x8& pa0, bf16x8& pa1, bf16x8& pa2, bf16x8& pa3) {
;     for (int r = 0; r < 16; ++r) p1[r] = __builtin_amdgcn_exp2f(p1[r]);
;     float ps = 0; for (int r = 0; r < 16; ++r) ps += p0[r]; for (int r = 0; r < 16; ++r) ps += p1[r];
;     { auto rr = __builtin_amdgcn_permlane32_swap(__float_as_uint(ps), __float_as_uint(ps), false, false);
;       ps = __uint_as_float(rr[0]) + __uint_as_float(rr[1]); }
;     l_reg = l_reg * alpha + ps;
;     ...
;     PK4(p0, 0, pa0); PK4(p0, 8, pa1); PK4(p1, 0, pa2); PK4(p1, 8, pa3);
;     ...
; }
; template <int KB>
; __device__ __forceinline__ void qkt(f32x16& p0, f32x16& p1, const char* K_lds, const float* bias_l, int r32, int hi, const bf16x8* qr) {
;     const f32x4* bl = reinterpret_cast<const f32x4*>(bias_l + KB * 64);
; #pragma unroll
;     for (int g = 0; g < 4; ++g) { const f32x4 b0 = bl[2 * g + hi], b1 = bl[8 + 2 * g + hi];
;         p0[4 * g + 0] = b0[0]; p0[4 * g + 1] = b0[1]; p0[4 * g + 2] = b0[2]; p0[4 * g + 3] = b0[3];
;         p1[4 * g + 0] = b1[0]; p1[4 * g + 1] = b1[1]; p1[4 * g + 2] = b1[2]; p1[4 * g + 3] = b1[3]; }
;     const char* kb[4];
; #pragma unroll
;     for (int dd = 0; dd < 4; ++dd) kb[dd] = K_lds + KB * SHM_K + KSWZ(r32, (dd * 16 + hi * 8) * 2);
; #pragma unroll
;     for (int d0 = 0; d0 < 8; ++d0) { const char* a = kb[d0 & 3] + (d0 >> 2) * 128;
;         bf16x8 b0 = *reinterpret_cast<const bf16x8*>(a);
;         bf16x8 b1 = *reinterpret_cast<const bf16x8*>(a + 32 * 256);
;         p0 = __builtin_amdgcn_mfma_f32_32x32x16_bf16(b0, qr[d0], p0, 0, 0, 0);
;         p1 = __builtin_amdgcn_mfma_f32_32x32x16_bf16(b1, qr[d0], p1, 0, 0, 0); }
; }
.LBB0_253:
	s_sub_i32 s12, s96, 64
	s_ashr_i32 s13, s12, 31
	s_lshl_b64 s[10:11], s[12:13], 8
	s_add_u32 s10, s77, s10
	s_addc_u32 s11, s80, s11
	s_add_u32 s14, s10, 0x2000
	s_addc_u32 s15, s11, 0
	s_add_u32 s16, s10, 0x2000000
	s_addc_u32 s17, s11, 0
	s_add_u32 s18, s10, 0x2002000
	s_addc_u32 s19, s11, 0
	v_lshlrev_b32_e32 v64, 1, v180
	global_load_dwordx4 v[160:163], v64, s[16:17]
	global_load_dwordx4 v[164:167], v64, s[10:11]
	global_load_dwordx4 v[168:171], v64, s[18:19]
	global_load_dwordx4 v[172:175], v64, s[14:15]
	s_andn2_b64 s[10:11], exec, s[2:3]
	s_andn2_b64 vcc, exec, s[2:3]
	s_cbranch_vccnz .LBB0_255
	v_lshl_add_u64 v[64:65], s[12:13], 3, v[192:193]
	global_load_dwordx2 v[188:189], v[64:65], off
.LBB0_255:
	ds_read_b128 v[84:87], v220
	ds_read_b128 v[88:91], v220 offset:32
	ds_read_b128 v[68:71], v220 offset:128
	ds_read_b128 v[72:75], v220 offset:160
	ds_read_b128 v[92:95], v220 offset:64
	ds_read_b128 v[76:79], v220 offset:192
	ds_read_b128 v[96:99], v220 offset:96
	ds_read_b128 v[80:83], v220 offset:224
	ds_read_b128 v[196:199], v214 offset:49152
	ds_read_b128 v[242:245], v214 offset:57344
	ds_read_b128 v[246:249], v215 offset:49152
	ds_read_b128 v[250:253], v215 offset:57344
	v_exp_f32_e32 v104, v126
	v_exp_f32_e32 v105, v127
	v_exp_f32_e32 v106, v124
	v_exp_f32_e32 v107, v125
	v_exp_f32_e32 v108, v122
	v_exp_f32_e32 v109, v123
	v_exp_f32_e32 v110, v120
	v_exp_f32_e32 v111, v121
	v_exp_f32_e32 v118, v118
	v_exp_f32_e32 v119, v119
	v_exp_f32_e32 v116, v116
	v_exp_f32_e32 v117, v117
	v_exp_f32_e32 v114, v114
	v_exp_f32_e32 v115, v115
	v_exp_f32_e32 v112, v112
	v_exp_f32_e32 v113, v113
	v_add_f32_e32 v64, 0, v237
	v_add_f32_e32 v64, v239, v64
	v_add_f32_e32 v64, v235, v64
	v_add_f32_e32 v64, v238, v64
	v_add_f32_e32 v64, v234, v64
	v_add_f32_e32 v64, v236, v64
	v_add_f32_e32 v64, v232, v64
	v_add_f32_e32 v64, v233, v64
	v_add_f32_e32 v64, v228, v64
	v_add_f32_e32 v64, v231, v64
	v_add_f32_e32 v64, v179, v64
	v_add_f32_e32 v64, v229, v64
	s_waitcnt lgkmcnt(2)
	v_mfma_f32_32x32x16_bf16 v[84:99], v[196:199], v[156:159], v[84:99]
	v_add_f32_e32 v64, v177, v64
	v_add_f32_e32 v64, v230, v64
	v_add_f32_e32 v64, v178, v64
	v_mfma_f32_32x32x16_bf16 v[68:83], v[242:245], v[156:159], v[68:83]
	v_add_f32_e32 v64, v227, v64
	v_add_f32_e32 v64, v104, v64
	v_add_f32_e32 v64, v105, v64
	ds_read_b128 v[196:199], v213 offset:49152
	ds_read_b128 v[242:245], v213 offset:57344
	s_waitcnt lgkmcnt(2)
	v_mfma_f32_32x32x16_bf16 v[84:99], v[246:249], v[152:155], v[84:99]
	v_add_f32_e32 v64, v106, v64
	v_add_f32_e32 v64, v107, v64
	v_add_f32_e32 v64, v108, v64
	v_mfma_f32_32x32x16_bf16 v[68:83], v[250:253], v[152:155], v[68:83]
	v_add_f32_e32 v64, v109, v64
	v_add_f32_e32 v64, v110, v64
	v_add_f32_e32 v64, v111, v64
	ds_read_b128 v[246:249], v212 offset:49152
	ds_read_b128 v[250:253], v212 offset:57344
	s_waitcnt lgkmcnt(2)
	v_mfma_f32_32x32x16_bf16 v[84:99], v[196:199], v[148:151], v[84:99]
	v_add_f32_e32 v64, v118, v64
	v_add_f32_e32 v64, v119, v64
	v_add_f32_e32 v64, v116, v64
	v_mfma_f32_32x32x16_bf16 v[68:83], v[242:245], v[148:151], v[68:83]
	v_add_f32_e32 v64, v117, v64
	v_add_f32_e32 v64, v114, v64
	v_add_f32_e32 v64, v115, v64
	ds_read_b128 v[196:199], v214 offset:49280
	ds_read_b128 v[242:245], v214 offset:57472
	s_waitcnt lgkmcnt(2)
	v_mfma_f32_32x32x16_bf16 v[84:99], v[246:249], v[144:147], v[84:99]
	v_add_f32_e32 v64, v112, v64
	v_add_f32_e32 v224, v113, v64
	v_mov_b32_e32 v225, v224
	v_mfma_f32_32x32x16_bf16 v[68:83], v[250:253], v[144:147], v[68:83]
	v_cvt_pk_bf16_f32 v64, v237, v239
	v_cvt_pk_bf16_f32 v65, v235, v238
	v_cvt_pk_bf16_f32 v66, v234, v236
	ds_read_b128 v[246:249], v215 offset:49280
	ds_read_b128 v[250:253], v215 offset:57472
	s_waitcnt lgkmcnt(2)
	v_mfma_f32_32x32x16_bf16 v[84:99], v[196:199], v[140:143], v[84:99]
	v_cvt_pk_bf16_f32 v67, v232, v233
	v_cvt_pk_bf16_f32 v100, v228, v231
	v_cvt_pk_bf16_f32 v101, v179, v229
	v_mfma_f32_32x32x16_bf16 v[68:83], v[242:245], v[140:143], v[68:83]
	v_cvt_pk_bf16_f32 v102, v177, v230
	v_cvt_pk_bf16_f32 v103, v178, v227
	v_cvt_pk_bf16_f32 v104, v104, v105
	ds_read_b128 v[196:199], v213 offset:49280
	ds_read_b128 v[242:245], v213 offset:57472
	s_waitcnt lgkmcnt(2)
	v_mfma_f32_32x32x16_bf16 v[84:99], v[246:249], v[136:139], v[84:99]
	v_cvt_pk_bf16_f32 v105, v106, v107
	v_cvt_pk_bf16_f32 v106, v108, v109
	v_cvt_pk_bf16_f32 v107, v110, v111
	v_mfma_f32_32x32x16_bf16 v[68:83], v[250:253], v[136:139], v[68:83]
	v_cvt_pk_bf16_f32 v108, v118, v119
	v_cvt_pk_bf16_f32 v109, v116, v117
	v_cvt_pk_bf16_f32 v110, v114, v115
	ds_read_b128 v[246:249], v212 offset:49280
	ds_read_b128 v[250:253], v212 offset:57472
	s_waitcnt lgkmcnt(2)
	v_mfma_f32_32x32x16_bf16 v[84:99], v[196:199], v[132:135], v[84:99]
	v_cvt_pk_bf16_f32 v111, v112, v113
	v_permlane32_swap_b32_e32 v224, v225
	v_permlane32_swap_b32_e32 v64, v66
	v_mfma_f32_32x32x16_bf16 v[68:83], v[242:245], v[132:135], v[68:83]
	v_permlane32_swap_b32_e32 v65, v67
	v_permlane32_swap_b32_e32 v100, v102
	v_permlane32_swap_b32_e32 v101, v103
	ds_read_b64_tr_b16 v[112:113], v209 offset:0x0
	ds_read_b64_tr_b16 v[114:115], v209 offset:0x800
	ds_read_b64_tr_b16 v[116:117], v209 offset:0x1000
	ds_read_b64_tr_b16 v[118:119], v209 offset:0x1800
	ds_read_b64_tr_b16 v[120:121], v209 offset:0x2000
	ds_read_b64_tr_b16 v[122:123], v209 offset:0x2800
	ds_read_b64_tr_b16 v[124:125], v209 offset:0x3000
	ds_read_b64_tr_b16 v[126:127], v209 offset:0x3800
	s_waitcnt lgkmcnt(8)
	v_mfma_f32_32x32x16_bf16 v[84:99], v[246:249], v[128:131], v[84:99]
	v_permlane32_swap_b32_e32 v104, v106
	v_permlane32_swap_b32_e32 v105, v107
	v_permlane32_swap_b32_e32 v108, v110
	v_mfma_f32_32x32x16_bf16 v[68:83], v[250:253], v[128:131], v[68:83]
	v_permlane32_swap_b32_e32 v109, v111
	s_add_i32 s12, s96, 0xffffffbf
	s_cmp_le_i32 s12, s84
	s_cbranch_scc1 .Lhs1_nomask
; __device__ __forceinline__ void mask_tile(f32x16& p0, f32x16& p1, int dq, unsigned W) {
;     const float NEG = -__builtin_inff();
; #pragma unroll
;     for (int r = 0; r < 16; ++r) {
;         const int c = (r & 3) + 8 * (r >> 2);
;         if ((unsigned)(dq - c) >= W) p0[r] = NEG;
;         if ((unsigned)(dq - c - 32) >= W) p1[r] = NEG;
;     }
; }
	v_add_u32_e32 v250, 64, v223
	v_cmp_gt_i32_e64 s[72:73], 26, v250
	v_cmp_gt_i32_e64 s[74:75], 27, v250
	v_cmp_gt_i32_e64 s[70:71], 25, v250
	s_and_b64 s[72:73], s[74:75], s[72:73]
	v_cmp_gt_i32_e64 s[68:69], 24, v250
	s_and_b64 s[70:71], s[72:73], s[70:71]
	v_cmp_gt_i32_e64 s[66:67], 19, v250
	s_and_b64 s[68:69], s[70:71], s[68:69]
	v_cmp_gt_i32_e64 s[64:65], 18, v250
	s_and_b64 s[66:67], s[68:69], s[66:67]
	v_cmp_gt_i32_e64 s[62:63], 17, v250
	s_and_b64 s[64:65], s[66:67], s[64:65]
	v_cmp_gt_i32_e64 s[60:61], 16, v250
	s_and_b64 s[62:63], s[64:65], s[62:63]
	v_cmp_gt_i32_e64 s[58:59], 11, v250
	s_and_b64 s[60:61], s[62:63], s[60:61]
	v_cmp_gt_i32_e64 s[56:57], 10, v250
	s_and_b64 s[58:59], s[60:61], s[58:59]
	v_cmp_gt_i32_e64 s[54:55], 9, v250
	s_and_b64 s[56:57], s[58:59], s[56:57]
	v_cmp_gt_i32_e64 s[52:53], 8, v250
	s_and_b64 s[54:55], s[56:57], s[54:55]
	v_cmp_gt_i32_e64 s[50:51], 3, v250
	s_and_b64 s[52:53], s[54:55], s[52:53]
	v_cmp_gt_i32_e64 s[48:49], 2, v250
	s_and_b64 s[50:51], s[52:53], s[50:51]
	v_cmp_gt_i32_e64 s[46:47], 1, v250
	s_and_b64 s[48:49], s[50:51], s[48:49]
	v_cmp_gt_i32_e64 s[44:45], 0, v250
	s_and_b64 s[46:47], s[48:49], s[46:47]
	s_and_b64 s[44:45], s[46:47], s[44:45]
	v_cmp_gt_i32_e64 s[40:41], 58, v250
	v_cndmask_b32_e64 v84, v84, v205, s[44:45]
	v_cmp_gt_i32_e64 s[44:45], 59, v250
	v_cmp_gt_i32_e64 s[38:39], 57, v250
	s_and_b64 s[40:41], s[44:45], s[40:41]
	v_cmp_gt_i32_e64 s[36:37], 56, v250
	s_and_b64 s[38:39], s[40:41], s[38:39]
	v_cmp_gt_i32_e64 s[34:35], 51, v250
	s_and_b64 s[36:37], s[38:39], s[36:37]
	v_cmp_gt_i32_e64 s[30:31], 50, v250
	s_and_b64 s[34:35], s[36:37], s[34:35]
	v_cmp_gt_i32_e64 s[28:29], 49, v250
	s_and_b64 s[30:31], s[34:35], s[30:31]
	v_cmp_gt_i32_e64 s[26:27], 48, v250
	s_and_b64 s[28:29], s[30:31], s[28:29]
	v_cmp_gt_i32_e64 s[24:25], 43, v250
	s_and_b64 s[26:27], s[28:29], s[26:27]
	v_cmp_gt_i32_e64 s[22:23], 42, v250
	s_and_b64 s[24:25], s[26:27], s[24:25]
	v_cmp_gt_i32_e64 s[20:21], 41, v250
	s_and_b64 s[22:23], s[24:25], s[22:23]
	v_cmp_gt_i32_e64 s[18:19], 40, v250
	s_and_b64 s[20:21], s[22:23], s[20:21]
	v_cmp_gt_i32_e64 s[16:17], 35, v250
	s_and_b64 s[18:19], s[20:21], s[18:19]
	v_cmp_gt_i32_e64 s[14:15], 34, v250
	s_and_b64 s[16:17], s[18:19], s[16:17]
	v_cmp_gt_i32_e64 s[12:13], 33, v250
	s_and_b64 s[14:15], s[16:17], s[14:15]
	v_cmp_gt_i32_e32 vcc, 32, v250
	s_and_b64 s[12:13], s[14:15], s[12:13]
	s_and_b64 vcc, s[12:13], vcc
	v_cndmask_b32_e64 v99, v99, v205, s[74:75]
	v_cndmask_b32_e64 v98, v98, v205, s[72:73]
	v_cndmask_b32_e64 v97, v97, v205, s[70:71]
	v_cndmask_b32_e64 v96, v96, v205, s[68:69]
	v_cndmask_b32_e64 v95, v95, v205, s[66:67]
	v_cndmask_b32_e64 v94, v94, v205, s[64:65]
	v_cndmask_b32_e64 v93, v93, v205, s[62:63]
	v_cndmask_b32_e64 v92, v92, v205, s[60:61]
	v_cndmask_b32_e64 v91, v91, v205, s[58:59]
	v_cndmask_b32_e64 v90, v90, v205, s[56:57]
	v_cndmask_b32_e64 v89, v89, v205, s[54:55]
	v_cndmask_b32_e64 v88, v88, v205, s[52:53]
	v_cndmask_b32_e64 v87, v87, v205, s[50:51]
	v_cndmask_b32_e64 v86, v86, v205, s[48:49]
	v_cndmask_b32_e64 v85, v85, v205, s[46:47]
	v_cndmask_b32_e64 v83, v83, v205, s[44:45]
	v_cndmask_b32_e64 v82, v82, v205, s[40:41]
	v_cndmask_b32_e64 v81, v81, v205, s[38:39]
	v_cndmask_b32_e64 v80, v80, v205, s[36:37]
	v_cndmask_b32_e64 v79, v79, v205, s[34:35]
	v_cndmask_b32_e64 v78, v78, v205, s[30:31]
	v_cndmask_b32_e64 v77, v77, v205, s[28:29]
	v_cndmask_b32_e64 v76, v76, v205, s[26:27]
	v_cndmask_b32_e64 v75, v75, v205, s[24:25]
	v_cndmask_b32_e64 v74, v74, v205, s[22:23]
	v_cndmask_b32_e64 v73, v73, v205, s[20:21]
	v_cndmask_b32_e64 v72, v72, v205, s[18:19]
	v_cndmask_b32_e64 v71, v71, v205, s[16:17]
	v_cndmask_b32_e64 v70, v70, v205, s[14:15]
	v_cndmask_b32_e64 v69, v69, v205, s[12:13]
	v_cndmask_b32_e32 v68, v68, v205, vcc
; __device__ __forceinline__ void partialSM(f32x16& p0, f32x16& p1, float& m_reg, float& mn, float& alpha) {
;     float pmax = p0[0]; for (int r = 1; r < 16; ++r) pmax = fmaxf(pmax, p0[r]); for (int r = 0; r < 16; ++r) pmax = fmaxf(pmax, p1[r]);
;     { auto rr = __builtin_amdgcn_permlane32_swap(__float_as_uint(pmax), __float_as_uint(pmax), false, false);
;       pmax = fmaxf(__uint_as_float(rr[0]), __uint_as_float(rr[1])); }
;     constexpr float C2 = 1.4426950408889634f * SCALE;
;     if (__builtin_expect(__all((pmax - m_reg) * SCALE <= THR), 1)) { mn = m_reg; alpha = 1.f; }
;     else { mn = fmaxf(m_reg, pmax); alpha = __builtin_amdgcn_exp2f((m_reg - mn) * C2); m_reg = mn; }
;     const float mnL = -mn * C2;
;     for (int r = 0; r < 16; ++r) p0[r] = fmaf(p0[r], C2, mnL); for (int r = 0; r < 16; ++r) p1[r] = fmaf(p1[r], C2, mnL);
;     for (int r = 0; r < 16; ++r) p0[r] = __builtin_amdgcn_exp2f(p0[r]);
; }
; template <int VB>
; __device__ __forceinline__ void pv_tile(f32x16* o, int vb0, bf16x8 pa0, bf16x8 pa1, bf16x8 pa2, bf16x8 pa3) {
;     ...
;     PV_D0(0); PV_D0(1); PV_D0(2); PV_D0(3);
.Lhs1_nomask:
	s_waitcnt lgkmcnt(4)
	v_mfma_f32_32x32x16_bf16 v[0:15], v[64:67], v[112:115], v[0:15]
	ds_read_b64_tr_b16 v[112:113], v209 offset:0x200
	ds_read_b64_tr_b16 v[114:115], v209 offset:0xa00
	v_mfma_f32_32x32x16_bf16 v[0:15], v[100:103], v[116:119], v[0:15]
	ds_read_b64_tr_b16 v[116:117], v209 offset:0x1200
	ds_read_b64_tr_b16 v[118:119], v209 offset:0x1a00
	s_waitcnt lgkmcnt(4)
	v_mfma_f32_32x32x16_bf16 v[0:15], v[104:107], v[120:123], v[0:15]
	ds_read_b64_tr_b16 v[120:121], v209 offset:0x2200
	ds_read_b64_tr_b16 v[122:123], v209 offset:0x2a00
	v_max_f32_e32 v250, v84, v85
	v_max3_f32 v250, v250, v86, v87
	v_max3_f32 v250, v250, v88, v89
	v_max3_f32 v250, v250, v90, v91
	v_max3_f32 v250, v250, v92, v93
	v_max3_f32 v250, v250, v94, v95
	v_max3_f32 v250, v250, v96, v97
	v_mfma_f32_32x32x16_bf16 v[0:15], v[108:111], v[124:127], v[0:15]
	ds_read_b64_tr_b16 v[124:125], v209 offset:0x3200
	ds_read_b64_tr_b16 v[126:127], v209 offset:0x3a00
	v_max3_f32 v250, v250, v98, v99
	v_max3_f32 v250, v250, v68, v69
	v_max3_f32 v250, v250, v70, v71
	v_max3_f32 v250, v250, v72, v73
	v_max3_f32 v250, v250, v74, v75
	v_max3_f32 v250, v250, v76, v77
	v_max3_f32 v250, v250, v78, v79
	s_waitcnt lgkmcnt(4)
	v_mfma_f32_32x32x16_bf16 v[48:63], v[64:67], v[112:115], v[48:63]
	ds_read_b64_tr_b16 v[112:113], v209 offset:0x400
	ds_read_b64_tr_b16 v[114:115], v209 offset:0xc00
	v_max3_f32 v250, v250, v80, v81
	v_max3_f32 v250, v250, v82, v83
	v_mov_b32_e32 v251, v250
	s_nop 1
	v_permlane32_swap_b32_e32 v250, v251
	v_max_f32_e32 v250, v250, v251
	v_sub_f32_e32 v251, v250, v176
	v_mul_f32_e32 v251, 0x3db504f3, v251
	v_mfma_f32_32x32x16_bf16 v[48:63], v[100:103], v[116:119], v[48:63]
	ds_read_b64_tr_b16 v[116:117], v209 offset:0x1400
	ds_read_b64_tr_b16 v[118:119], v209 offset:0x1c00
	v_cmp_ge_f32_e32 vcc, s97, v251
	s_cmp_eq_u64 vcc, exec
	s_cbranch_scc0 .Lhs1_slow
	v_mov_b32_e32 v226, 1.0
	v_mov_b32_e32 v227, v176
.Lhs1_join:
	v_mul_f32_e32 v176, 0xbe0293ee, v227
	v_fmamk_f32 v196, v84, 0x3e0293ee, v176
	s_waitcnt lgkmcnt(4)
	v_mfma_f32_32x32x16_bf16 v[48:63], v[104:107], v[120:123], v[48:63]
	ds_read_b64_tr_b16 v[120:121], v209 offset:0x2400
	ds_read_b64_tr_b16 v[122:123], v209 offset:0x2c00
	v_fmamk_f32 v197, v85, 0x3e0293ee, v176
	v_fmamk_f32 v198, v86, 0x3e0293ee, v176
	v_fmamk_f32 v199, v87, 0x3e0293ee, v176
	v_fmamk_f32 v242, v88, 0x3e0293ee, v176
	v_fmamk_f32 v243, v89, 0x3e0293ee, v176
	v_fmamk_f32 v244, v90, 0x3e0293ee, v176
	v_fmamk_f32 v245, v91, 0x3e0293ee, v176
	v_mfma_f32_32x32x16_bf16 v[48:63], v[108:111], v[124:127], v[48:63]
	ds_read_b64_tr_b16 v[124:125], v209 offset:0x3400
	ds_read_b64_tr_b16 v[126:127], v209 offset:0x3c00
	v_fmamk_f32 v246, v92, 0x3e0293ee, v176
	v_fmamk_f32 v247, v93, 0x3e0293ee, v176
	v_fmamk_f32 v248, v94, 0x3e0293ee, v176
	v_fmamk_f32 v249, v95, 0x3e0293ee, v176
	v_fmamk_f32 v96, v96, 0x3e0293ee, v176
	v_fmamk_f32 v97, v97, 0x3e0293ee, v176
	v_fmamk_f32 v98, v98, 0x3e0293ee, v176
	s_waitcnt lgkmcnt(4)
	v_mfma_f32_32x32x16_bf16 v[32:47], v[64:67], v[112:115], v[32:47]
	ds_read_b64_tr_b16 v[112:113], v209 offset:0x600
	ds_read_b64_tr_b16 v[114:115], v209 offset:0xe00
	v_fmamk_f32 v99, v99, 0x3e0293ee, v176
	v_fmamk_f32 v84, v68, 0x3e0293ee, v176
	v_fmamk_f32 v93, v69, 0x3e0293ee, v176
	v_fmamk_f32 v94, v70, 0x3e0293ee, v176
	v_fmamk_f32 v95, v71, 0x3e0293ee, v176
	v_fmamk_f32 v177, v72, 0x3e0293ee, v176
	v_fmamk_f32 v85, v73, 0x3e0293ee, v176
	v_mfma_f32_32x32x16_bf16 v[32:47], v[100:103], v[116:119], v[32:47]
	ds_read_b64_tr_b16 v[116:117], v209 offset:0x1600
	ds_read_b64_tr_b16 v[118:119], v209 offset:0x1e00
	v_fmamk_f32 v86, v74, 0x3e0293ee, v176
	v_fmamk_f32 v87, v75, 0x3e0293ee, v176
	v_fmamk_f32 v88, v76, 0x3e0293ee, v176
	v_fmamk_f32 v89, v77, 0x3e0293ee, v176
	v_fmamk_f32 v90, v78, 0x3e0293ee, v176
	v_fmamk_f32 v91, v79, 0x3e0293ee, v176
	v_fmamk_f32 v92, v80, 0x3e0293ee, v176
	s_waitcnt lgkmcnt(4)
	v_mfma_f32_32x32x16_bf16 v[32:47], v[104:107], v[120:123], v[32:47]
	ds_read_b64_tr_b16 v[120:121], v209 offset:0x2600
	ds_read_b64_tr_b16 v[122:123], v209 offset:0x2e00
	v_fmamk_f32 v178, v81, 0x3e0293ee, v176
	v_fmamk_f32 v179, v82, 0x3e0293ee, v176
	v_fmac_f32_e32 v176, 0x3e0293ee, v83
	v_exp_f32_e32 v68, v242
	v_exp_f32_e32 v69, v243
	v_mfma_f32_32x32x16_bf16 v[32:47], v[108:111], v[124:127], v[32:47]
	ds_read_b64_tr_b16 v[124:125], v209 offset:0x3600
	ds_read_b64_tr_b16 v[126:127], v209 offset:0x3e00
	v_exp_f32_e32 v70, v244
	v_exp_f32_e32 v71, v245
	v_exp_f32_e32 v72, v246
	v_exp_f32_e32 v73, v247
	s_waitcnt lgkmcnt(4)
	v_mfma_f32_32x32x16_bf16 v[16:31], v[64:67], v[112:115], v[16:31]
	v_exp_f32_e32 v74, v248
	v_exp_f32_e32 v75, v249
	v_exp_f32_e32 v76, v96
	v_exp_f32_e32 v77, v97
	v_mfma_f32_32x32x16_bf16 v[16:31], v[100:103], v[116:119], v[16:31]
	v_exp_f32_e32 v78, v98
	v_exp_f32_e32 v79, v99
	s_waitcnt lgkmcnt(0)
	v_mfma_f32_32x32x16_bf16 v[16:31], v[104:107], v[120:123], v[16:31]
	v_mfma_f32_32x32x16_bf16 v[16:31], v[108:111], v[124:127], v[16:31]
	s_waitcnt vmcnt(0)
	s_and_b64 vcc, exec, s[10:11]
	ds_write_b128 v208, v[164:167] offset:32768
	ds_write_b128 v208, v[172:175] offset:40960
	s_cbranch_vccnz .Lhs1_nobias
	s_mov_b32 s14, 0x667f3bcd
	v_add_f64 v[66:67], s[94:95], -v[188:189]
	s_mov_b32 s15, 0x4026a09e
	v_mul_f64 v[66:67], v[66:67], s[14:15]
	v_cvt_f32_f64_e32 v65, v[66:67]
	ds_write_b32 v221, v65

.Lhs1_norescale:
	s_waitcnt lgkmcnt(0)
	s_barrier
	s_add_i32 s12, s83, 1
	s_cmp_lt_i32 s12, s89
	s_cselect_b64 s[42:43], -1, 0
	s_cmp_ge_i32 s12, s89
	s_cbranch_scc1 .LBB0_267
	s_ashr_i32 s97, s96, 31
	s_lshl_b64 s[12:13], s[96:97], 8
	s_add_u32 s12, s77, s12
	s_addc_u32 s13, s80, s13
	s_add_u32 s14, s12, 0x2000
	s_addc_u32 s15, s13, 0
	s_add_u32 s16, s12, 0x2000000
	s_addc_u32 s17, s13, 0
	s_add_u32 s18, s12, 0x2002000
	s_addc_u32 s19, s13, 0
	v_lshlrev_b32_e32 v80, 1, v180
	global_load_dwordx4 v[160:163], v80, s[16:17]
	global_load_dwordx4 v[164:167], v80, s[12:13]
	global_load_dwordx4 v[168:171], v80, s[18:19]
	global_load_dwordx4 v[172:175], v80, s[14:15]
	s_and_b64 vcc, exec, s[10:11]
	s_cbranch_vccnz .LBB0_266
	v_lshl_add_u64 v[80:81], s[96:97], 3, v[192:193]
	global_load_dwordx2 v[188:189], v[80:81], off

; __device__ __forceinline__ void finishSM(f32x16& p0, f32x16& p1, float alpha, float& l_reg, bf16x8& pa0, bf16x8& pa1, bf16x8& pa2, bf16x8& pa3) {
;     for (int r = 0; r < 16; ++r) p1[r] = __builtin_amdgcn_exp2f(p1[r]);
;     float ps = 0; for (int r = 0; r < 16; ++r) ps += p0[r]; for (int r = 0; r < 16; ++r) ps += p1[r];
;     { auto rr = __builtin_amdgcn_permlane32_swap(__float_as_uint(ps), __float_as_uint(ps), false, false);
;       ps = __uint_as_float(rr[0]) + __uint_as_float(rr[1]); }
;     l_reg = l_reg * alpha + ps;
;     ...
;     PK4(p0, 0, pa0); PK4(p0, 8, pa1); PK4(p1, 0, pa2); PK4(p1, 8, pa3);
;     ...
; }
; template <int KB>
; __device__ __forceinline__ void qkt(f32x16& p0, f32x16& p1, const char* K_lds, const float* bias_l, int r32, int hi, const bf16x8* qr) {
;     const f32x4* bl = reinterpret_cast<const f32x4*>(bias_l + KB * 64);
; #pragma unroll
;     for (int g = 0; g < 4; ++g) { const f32x4 b0 = bl[2 * g + hi], b1 = bl[8 + 2 * g + hi];
;         p0[4 * g + 0] = b0[0]; p0[4 * g + 1] = b0[1]; p0[4 * g + 2] = b0[2]; p0[4 * g + 3] = b0[3];
;         p1[4 * g + 0] = b1[0]; p1[4 * g + 1] = b1[1]; p1[4 * g + 2] = b1[2]; p1[4 * g + 3] = b1[3]; }
;     const char* kb[4];
; #pragma unroll
;     for (int dd = 0; dd < 4; ++dd) kb[dd] = K_lds + KB * SHM_K + KSWZ(r32, (dd * 16 + hi * 8) * 2);
; #pragma unroll
;     for (int d0 = 0; d0 < 8; ++d0) { const char* a = kb[d0 & 3] + (d0 >> 2) * 128;
;         bf16x8 b0 = *reinterpret_cast<const bf16x8*>(a);
;         bf16x8 b1 = *reinterpret_cast<const bf16x8*>(a + 32 * 256);
;         p0 = __builtin_amdgcn_mfma_f32_32x32x16_bf16(b0, qr[d0], p0, 0, 0, 0);
;         p1 = __builtin_amdgcn_mfma_f32_32x32x16_bf16(b1, qr[d0], p1, 0, 0, 0); }
; }
.LBB0_267:
	ds_read_b128 v[112:115], v219
	ds_read_b128 v[116:119], v219 offset:32
	ds_read_b128 v[96:99], v219 offset:128
	ds_read_b128 v[100:103], v219 offset:160
	ds_read_b128 v[120:123], v219 offset:64
	ds_read_b128 v[104:107], v219 offset:192
	ds_read_b128 v[124:127], v219 offset:96
	ds_read_b128 v[108:111], v219 offset:224
	ds_read_b128 v[196:199], v214 offset:32768
	ds_read_b128 v[242:245], v214 offset:40960
	ds_read_b128 v[246:249], v215 offset:32768
	ds_read_b128 v[250:253], v215 offset:40960
	v_exp_f32_e32 v85, v85
	v_exp_f32_e32 v86, v86
	v_exp_f32_e32 v87, v87
	v_exp_f32_e32 v88, v88
	v_exp_f32_e32 v89, v89
	v_exp_f32_e32 v90, v90
	v_exp_f32_e32 v91, v91
	v_exp_f32_e32 v92, v92
	v_exp_f32_e32 v83, v95
	v_exp_f32_e32 v95, v176
	v_exp_f32_e32 v80, v84
	v_exp_f32_e32 v81, v93
	v_exp_f32_e32 v82, v94
	v_exp_f32_e32 v84, v177
	v_exp_f32_e32 v93, v178
	v_exp_f32_e32 v94, v179
	v_add_f32_e32 v176, 0, v64
	v_add_f32_e32 v176, v65, v176
	v_add_f32_e32 v176, v66, v176
	v_add_f32_e32 v176, v67, v176
	v_add_f32_e32 v176, v68, v176
	v_add_f32_e32 v176, v69, v176
	v_add_f32_e32 v176, v70, v176
	v_add_f32_e32 v176, v71, v176
	v_add_f32_e32 v176, v72, v176
	v_add_f32_e32 v176, v73, v176
	v_add_f32_e32 v176, v74, v176
	v_add_f32_e32 v176, v75, v176
	s_waitcnt lgkmcnt(2)
	v_mfma_f32_32x32x16_bf16 v[112:127], v[196:199], v[156:159], v[112:127]
	v_add_f32_e32 v176, v76, v176
	v_add_f32_e32 v176, v77, v176
	v_add_f32_e32 v176, v78, v176
	v_mfma_f32_32x32x16_bf16 v[96:111], v[242:245], v[156:159], v[96:111]
	v_add_f32_e32 v176, v79, v176
	v_add_f32_e32 v176, v80, v176
	v_add_f32_e32 v176, v81, v176
	ds_read_b128 v[196:199], v213 offset:32768
	ds_read_b128 v[242:245], v213 offset:40960
	s_waitcnt lgkmcnt(2)
	v_mfma_f32_32x32x16_bf16 v[112:127], v[246:249], v[152:155], v[112:127]
	v_add_f32_e32 v176, v82, v176
	v_add_f32_e32 v176, v83, v176
	v_add_f32_e32 v176, v84, v176
	v_mfma_f32_32x32x16_bf16 v[96:111], v[250:253], v[152:155], v[96:111]
	v_add_f32_e32 v176, v85, v176
	v_add_f32_e32 v176, v86, v176
	v_add_f32_e32 v176, v87, v176
	ds_read_b128 v[246:249], v212 offset:32768
	ds_read_b128 v[250:253], v212 offset:40960
	s_waitcnt lgkmcnt(2)
	v_mfma_f32_32x32x16_bf16 v[112:127], v[196:199], v[148:151], v[112:127]
	v_add_f32_e32 v176, v88, v176
	v_add_f32_e32 v176, v89, v176
	v_add_f32_e32 v176, v90, v176
	v_mfma_f32_32x32x16_bf16 v[96:111], v[242:245], v[148:151], v[96:111]
	v_add_f32_e32 v176, v91, v176
	v_add_f32_e32 v176, v92, v176
	v_add_f32_e32 v176, v93, v176
	ds_read_b128 v[196:199], v214 offset:32896
	ds_read_b128 v[242:245], v214 offset:41088
	s_waitcnt lgkmcnt(2)
	v_mfma_f32_32x32x16_bf16 v[112:127], v[246:249], v[144:147], v[112:127]
	v_add_f32_e32 v176, v94, v176
	v_add_f32_e32 v240, v95, v176
	v_mov_b32_e32 v241, v240
	v_mfma_f32_32x32x16_bf16 v[96:111], v[250:253], v[144:147], v[96:111]
	v_cvt_pk_bf16_f32 v64, v64, v65
	v_cvt_pk_bf16_f32 v65, v66, v67
	v_cvt_pk_bf16_f32 v66, v68, v69
	ds_read_b128 v[246:249], v215 offset:32896
	ds_read_b128 v[250:253], v215 offset:41088
	s_waitcnt lgkmcnt(2)
	v_mfma_f32_32x32x16_bf16 v[112:127], v[196:199], v[140:143], v[112:127]
	v_cvt_pk_bf16_f32 v67, v70, v71
	v_cvt_pk_bf16_f32 v68, v72, v73
	v_cvt_pk_bf16_f32 v69, v74, v75
	v_mfma_f32_32x32x16_bf16 v[96:111], v[242:245], v[140:143], v[96:111]
	v_cvt_pk_bf16_f32 v70, v76, v77
	v_cvt_pk_bf16_f32 v71, v78, v79
	v_cvt_pk_bf16_f32 v72, v80, v81
	ds_read_b128 v[196:199], v213 offset:32896
	ds_read_b128 v[242:245], v213 offset:41088
	s_waitcnt lgkmcnt(2)
	v_mfma_f32_32x32x16_bf16 v[112:127], v[246:249], v[136:139], v[112:127]
	v_cvt_pk_bf16_f32 v73, v82, v83
	v_cvt_pk_bf16_f32 v74, v84, v85
	v_cvt_pk_bf16_f32 v75, v86, v87
	v_mfma_f32_32x32x16_bf16 v[96:111], v[250:253], v[136:139], v[96:111]
	v_cvt_pk_bf16_f32 v76, v88, v89
	v_cvt_pk_bf16_f32 v77, v90, v91
	v_cvt_pk_bf16_f32 v78, v92, v93
	ds_read_b128 v[246:249], v212 offset:32896
	ds_read_b128 v[250:253], v212 offset:41088
	s_waitcnt lgkmcnt(2)
	v_mfma_f32_32x32x16_bf16 v[112:127], v[196:199], v[132:135], v[112:127]
	v_cvt_pk_bf16_f32 v79, v94, v95
	v_permlane32_swap_b32_e32 v240, v241
	v_permlane32_swap_b32_e32 v64, v66
	v_mfma_f32_32x32x16_bf16 v[96:111], v[242:245], v[132:135], v[96:111]
	v_permlane32_swap_b32_e32 v65, v67
	v_permlane32_swap_b32_e32 v68, v70
	v_permlane32_swap_b32_e32 v69, v71
	ds_read_b64_tr_b16 v[196:197], v209 offset:0x4000
	ds_read_b64_tr_b16 v[198:199], v209 offset:0x4800
	ds_read_b64_tr_b16 v[242:243], v209 offset:0x5000
	ds_read_b64_tr_b16 v[244:245], v209 offset:0x5800
	s_waitcnt lgkmcnt(4)
	v_mfma_f32_32x32x16_bf16 v[112:127], v[246:249], v[128:131], v[112:127]
	v_permlane32_swap_b32_e32 v72, v74
	v_permlane32_swap_b32_e32 v73, v75
	v_permlane32_swap_b32_e32 v76, v78
	v_mfma_f32_32x32x16_bf16 v[96:111], v[250:253], v[128:131], v[96:111]
	v_permlane32_swap_b32_e32 v77, v79
	ds_read_b64_tr_b16 v[246:247], v209 offset:0x6000
	ds_read_b64_tr_b16 v[248:249], v209 offset:0x6800
	ds_read_b64_tr_b16 v[250:251], v209 offset:0x7000
	ds_read_b64_tr_b16 v[252:253], v209 offset:0x7800
	s_add_i32 s12, s96, -1
	s_cmp_le_i32 s12, s84
	s_cbranch_scc1 .Lhs2_nomask
; __device__ __forceinline__ void mask_tile(f32x16& p0, f32x16& p1, int dq, unsigned W) {
;     const float NEG = -__builtin_inff();
; #pragma unroll
;     for (int r = 0; r < 16; ++r) {
;         const int c = (r & 3) + 8 * (r >> 2);
;         if ((unsigned)(dq - c) >= W) p0[r] = NEG;
;         if ((unsigned)(dq - c - 32) >= W) p1[r] = NEG;
;     }
; }
; __device__ __forceinline__ void partialSM(f32x16& p0, f32x16& p1, float& m_reg, float& mn, float& alpha) {
;     float pmax = p0[0]; for (int r = 1; r < 16; ++r) pmax = fmaxf(pmax, p0[r]); for (int r = 0; r < 16; ++r) pmax = fmaxf(pmax, p1[r]);
;     { auto rr = __builtin_amdgcn_permlane32_swap(__float_as_uint(pmax), __float_as_uint(pmax), false, false);
;       pmax = fmaxf(__uint_as_float(rr[0]), __uint_as_float(rr[1])); }
;     constexpr float C2 = 1.4426950408889634f * SCALE;
;     if (__builtin_expect(__all((pmax - m_reg) * SCALE <= THR), 1)) { mn = m_reg; alpha = 1.f; }
;     else { mn = fmaxf(m_reg, pmax); alpha = __builtin_amdgcn_exp2f((m_reg - mn) * C2); m_reg = mn; }
;     const float mnL = -mn * C2;
;     for (int r = 0; r < 16; ++r) p0[r] = fmaf(p0[r], C2, mnL); for (int r = 0; r < 16; ++r) p1[r] = fmaf(p1[r], C2, mnL);
;     for (int r = 0; r < 16; ++r) p0[r] = __builtin_amdgcn_exp2f(p0[r]);
; }
	v_cmp_gt_i32_e64 s[72:73], 26, v223
	v_cmp_gt_i32_e64 s[74:75], 27, v223
	v_cmp_gt_i32_e64 s[70:71], 25, v223
	s_and_b64 s[72:73], s[74:75], s[72:73]
	v_cmp_gt_i32_e64 s[68:69], 24, v223
	s_and_b64 s[70:71], s[72:73], s[70:71]
	v_cmp_gt_i32_e64 s[66:67], 19, v223
	s_and_b64 s[68:69], s[70:71], s[68:69]
	v_cmp_gt_i32_e64 s[64:65], 18, v223
	s_and_b64 s[66:67], s[68:69], s[66:67]
	v_cmp_gt_i32_e64 s[62:63], 17, v223
	s_and_b64 s[64:65], s[66:67], s[64:65]
	v_cmp_gt_i32_e64 s[60:61], 16, v223
	s_and_b64 s[62:63], s[64:65], s[62:63]
	v_cmp_gt_i32_e64 s[58:59], 11, v223
	s_and_b64 s[60:61], s[62:63], s[60:61]
	v_cmp_gt_i32_e64 s[56:57], 10, v223
	s_and_b64 s[58:59], s[60:61], s[58:59]
	v_cmp_gt_i32_e64 s[54:55], 9, v223
	s_and_b64 s[56:57], s[58:59], s[56:57]
	v_cmp_gt_i32_e64 s[52:53], 8, v223
	s_and_b64 s[54:55], s[56:57], s[54:55]
	v_cmp_gt_i32_e64 s[50:51], 3, v223
	s_and_b64 s[52:53], s[54:55], s[52:53]
	v_cmp_gt_i32_e64 s[48:49], 2, v223
	s_and_b64 s[50:51], s[52:53], s[50:51]
	v_cmp_gt_i32_e64 s[46:47], 1, v223
	s_and_b64 s[48:49], s[50:51], s[48:49]
	v_cmp_gt_i32_e64 s[44:45], 0, v223
	s_and_b64 s[46:47], s[48:49], s[46:47]
	s_and_b64 s[44:45], s[46:47], s[44:45]
	v_cmp_gt_i32_e64 s[40:41], 58, v223
	v_cndmask_b32_e64 v112, v112, v205, s[44:45]
	v_cmp_gt_i32_e64 s[44:45], 59, v223
	v_cmp_gt_i32_e64 s[38:39], 57, v223
	s_and_b64 s[40:41], s[44:45], s[40:41]
	v_cmp_gt_i32_e64 s[36:37], 56, v223
	s_and_b64 s[38:39], s[40:41], s[38:39]
	v_cmp_gt_i32_e64 s[34:35], 51, v223
	s_and_b64 s[36:37], s[38:39], s[36:37]
	v_cmp_gt_i32_e64 s[30:31], 50, v223
	s_and_b64 s[34:35], s[36:37], s[34:35]
	v_cmp_gt_i32_e64 s[28:29], 49, v223
	s_and_b64 s[30:31], s[34:35], s[30:31]
	v_cmp_gt_i32_e64 s[26:27], 48, v223
	s_and_b64 s[28:29], s[30:31], s[28:29]
	v_cmp_gt_i32_e64 s[24:25], 43, v223
	s_and_b64 s[26:27], s[28:29], s[26:27]
	v_cmp_gt_i32_e64 s[22:23], 42, v223
	s_and_b64 s[24:25], s[26:27], s[24:25]
	v_cmp_gt_i32_e64 s[20:21], 41, v223
	s_and_b64 s[22:23], s[24:25], s[22:23]
	v_cmp_gt_i32_e64 s[18:19], 40, v223
	s_and_b64 s[20:21], s[22:23], s[20:21]
	v_cmp_gt_i32_e64 s[16:17], 35, v223
	s_and_b64 s[18:19], s[20:21], s[18:19]
	v_cmp_gt_i32_e64 s[14:15], 34, v223
	s_and_b64 s[16:17], s[18:19], s[16:17]
	v_cmp_gt_i32_e64 s[12:13], 33, v223
	s_and_b64 s[14:15], s[16:17], s[14:15]
	v_cmp_gt_i32_e32 vcc, 32, v223
	s_and_b64 s[12:13], s[14:15], s[12:13]
	s_and_b64 vcc, s[12:13], vcc
	v_cndmask_b32_e64 v127, v127, v205, s[74:75]
	v_cndmask_b32_e64 v126, v126, v205, s[72:73]
	v_cndmask_b32_e64 v125, v125, v205, s[70:71]
	v_cndmask_b32_e64 v124, v124, v205, s[68:69]
	v_cndmask_b32_e64 v123, v123, v205, s[66:67]
	v_cndmask_b32_e64 v122, v122, v205, s[64:65]
	v_cndmask_b32_e64 v121, v121, v205, s[62:63]
	v_cndmask_b32_e64 v120, v120, v205, s[60:61]
	v_cndmask_b32_e64 v119, v119, v205, s[58:59]
	v_cndmask_b32_e64 v118, v118, v205, s[56:57]
	v_cndmask_b32_e64 v117, v117, v205, s[54:55]
	v_cndmask_b32_e64 v116, v116, v205, s[52:53]
	v_cndmask_b32_e64 v115, v115, v205, s[50:51]
	v_cndmask_b32_e64 v114, v114, v205, s[48:49]
	v_cndmask_b32_e64 v113, v113, v205, s[46:47]
	v_cndmask_b32_e64 v111, v111, v205, s[44:45]
	v_cndmask_b32_e64 v110, v110, v205, s[40:41]
	v_cndmask_b32_e64 v109, v109, v205, s[38:39]
	v_cndmask_b32_e64 v108, v108, v205, s[36:37]
	v_cndmask_b32_e64 v107, v107, v205, s[34:35]
	v_cndmask_b32_e64 v106, v106, v205, s[30:31]
	v_cndmask_b32_e64 v105, v105, v205, s[28:29]
	v_cndmask_b32_e64 v104, v104, v205, s[26:27]
	v_cndmask_b32_e64 v103, v103, v205, s[24:25]
	v_cndmask_b32_e64 v102, v102, v205, s[22:23]
	v_cndmask_b32_e64 v101, v101, v205, s[20:21]
	v_cndmask_b32_e64 v100, v100, v205, s[18:19]
	v_cndmask_b32_e64 v99, v99, v205, s[16:17]
	v_cndmask_b32_e64 v98, v98, v205, s[14:15]
	v_cndmask_b32_e64 v97, v97, v205, s[12:13]
	v_cndmask_b32_e32 v96, v96, v205, vcc
.Lhs2_nomask:
	s_waitcnt lgkmcnt(4)
	v_mfma_f32_32x32x16_bf16 v[0:15], v[64:67], v[196:199], v[0:15]
	ds_read_b64_tr_b16 v[196:197], v209 offset:0x4200
	ds_read_b64_tr_b16 v[198:199], v209 offset:0x4a00
	v_mfma_f32_32x32x16_bf16 v[0:15], v[68:71], v[242:245], v[0:15]
	ds_read_b64_tr_b16 v[242:243], v209 offset:0x5200
	ds_read_b64_tr_b16 v[244:245], v209 offset:0x5a00
	s_waitcnt lgkmcnt(4)
	v_mfma_f32_32x32x16_bf16 v[0:15], v[72:75], v[246:249], v[0:15]
	ds_read_b64_tr_b16 v[246:247], v209 offset:0x6200
	ds_read_b64_tr_b16 v[248:249], v209 offset:0x6a00
	v_max_f32_e32 v176, v112, v113
	v_max3_f32 v176, v176, v114, v115
	v_max3_f32 v176, v176, v116, v117
	v_max3_f32 v176, v176, v118, v119
	v_max3_f32 v176, v176, v120, v121
	v_max3_f32 v176, v176, v122, v123
	v_max3_f32 v176, v176, v124, v125
	v_max3_f32 v176, v176, v126, v127
	v_mfma_f32_32x32x16_bf16 v[0:15], v[76:79], v[250:253], v[0:15]
	ds_read_b64_tr_b16 v[250:251], v209 offset:0x7200
	ds_read_b64_tr_b16 v[252:253], v209 offset:0x7a00
	v_max3_f32 v176, v176, v96, v97
	v_max3_f32 v176, v176, v98, v99
	v_max3_f32 v176, v176, v100, v101
	v_max3_f32 v176, v176, v102, v103
	v_max3_f32 v176, v176, v104, v105
	v_max3_f32 v176, v176, v106, v107
	v_max3_f32 v176, v176, v108, v109
	v_max3_f32 v176, v176, v110, v111
	s_waitcnt lgkmcnt(4)
	v_mfma_f32_32x32x16_bf16 v[48:63], v[64:67], v[196:199], v[48:63]
	ds_read_b64_tr_b16 v[196:197], v209 offset:0x4400
	ds_read_b64_tr_b16 v[198:199], v209 offset:0x4c00
	v_mov_b32_e32 v177, v176
	s_nop 1
	v_permlane32_swap_b32_e32 v176, v177
	v_max_f32_e32 v176, v176, v177
	v_sub_f32_e32 v177, v176, v227
	v_mul_f32_e32 v177, 0x3db504f3, v177
	v_cmp_ge_f32_e32 vcc, s97, v177
	s_cmp_eq_u64 vcc, exec
	s_cbranch_scc0 .Lhs2_slow
	v_mov_b32_e32 v179, 1.0
	v_mov_b32_e32 v176, v227
; __device__ __forceinline__ void partialSM(f32x16& p0, f32x16& p1, float& m_reg, float& mn, float& alpha) {
;     float pmax = p0[0]; for (int r = 1; r < 16; ++r) pmax = fmaxf(pmax, p0[r]); for (int r = 0; r < 16; ++r) pmax = fmaxf(pmax, p1[r]);
;     { auto rr = __builtin_amdgcn_permlane32_swap(__float_as_uint(pmax), __float_as_uint(pmax), false, false);
;       pmax = fmaxf(__uint_as_float(rr[0]), __uint_as_float(rr[1])); }
;     constexpr float C2 = 1.4426950408889634f * SCALE;
;     if (__builtin_expect(__all((pmax - m_reg) * SCALE <= THR), 1)) { mn = m_reg; alpha = 1.f; }
;     else { mn = fmaxf(m_reg, pmax); alpha = __builtin_amdgcn_exp2f((m_reg - mn) * C2); m_reg = mn; }
;     const float mnL = -mn * C2;
;     for (int r = 0; r < 16; ++r) p0[r] = fmaf(p0[r], C2, mnL); for (int r = 0; r < 16; ++r) p1[r] = fmaf(p1[r], C2, mnL);
;     for (int r = 0; r < 16; ++r) p0[r] = __builtin_amdgcn_exp2f(p0[r]);
; }
; template <int VB>
; __device__ __forceinline__ void pv_tile(f32x16* o, int vb0, bf16x8 pa0, bf16x8 pa1, bf16x8 pa2, bf16x8 pa3) {
;     ...
;     PV_D0(0); PV_D0(1); PV_D0(2); PV_D0(3);
.Lhs2_join:
	v_mul_f32_e32 v178, 0xbe0293ee, v176
	v_mfma_f32_32x32x16_bf16 v[48:63], v[68:71], v[242:245], v[48:63]
	ds_read_b64_tr_b16 v[242:243], v209 offset:0x5400
	ds_read_b64_tr_b16 v[244:245], v209 offset:0x5c00
	v_fmamk_f32 v80, v112, 0x3e0293ee, v178
	v_fmamk_f32 v81, v113, 0x3e0293ee, v178
	v_fmamk_f32 v82, v114, 0x3e0293ee, v178
	v_fmamk_f32 v83, v115, 0x3e0293ee, v178
	v_fmamk_f32 v84, v116, 0x3e0293ee, v178
	v_fmamk_f32 v85, v117, 0x3e0293ee, v178
	v_fmamk_f32 v86, v118, 0x3e0293ee, v178
	v_fmamk_f32 v87, v119, 0x3e0293ee, v178
	s_waitcnt lgkmcnt(4)
	v_mfma_f32_32x32x16_bf16 v[48:63], v[72:75], v[246:249], v[48:63]
	ds_read_b64_tr_b16 v[246:247], v209 offset:0x6400
	ds_read_b64_tr_b16 v[248:249], v209 offset:0x6c00
	v_fmamk_f32 v88, v120, 0x3e0293ee, v178
	v_fmamk_f32 v89, v121, 0x3e0293ee, v178
	v_fmamk_f32 v90, v122, 0x3e0293ee, v178
	v_fmamk_f32 v91, v123, 0x3e0293ee, v178
	v_fmamk_f32 v92, v124, 0x3e0293ee, v178
	v_fmamk_f32 v93, v125, 0x3e0293ee, v178
	v_fmamk_f32 v94, v126, 0x3e0293ee, v178
	v_fmamk_f32 v95, v127, 0x3e0293ee, v178
	v_mfma_f32_32x32x16_bf16 v[48:63], v[76:79], v[250:253], v[48:63]
	ds_read_b64_tr_b16 v[250:251], v209 offset:0x7400
	ds_read_b64_tr_b16 v[252:253], v209 offset:0x7c00
	v_fmamk_f32 v126, v96, 0x3e0293ee, v178
	v_fmamk_f32 v127, v97, 0x3e0293ee, v178
	v_fmamk_f32 v112, v110, 0x3e0293ee, v178
	v_fmamk_f32 v113, v111, 0x3e0293ee, v178
	v_fmamk_f32 v114, v108, 0x3e0293ee, v178
	v_fmamk_f32 v115, v109, 0x3e0293ee, v178
	v_fmamk_f32 v116, v106, 0x3e0293ee, v178
	v_fmamk_f32 v117, v107, 0x3e0293ee, v178
	s_waitcnt lgkmcnt(4)
	v_mfma_f32_32x32x16_bf16 v[32:47], v[64:67], v[196:199], v[32:47]
	ds_read_b64_tr_b16 v[196:197], v209 offset:0x4600
	ds_read_b64_tr_b16 v[198:199], v209 offset:0x4e00
	v_fmamk_f32 v118, v104, 0x3e0293ee, v178
	v_fmamk_f32 v119, v105, 0x3e0293ee, v178
	v_fmamk_f32 v120, v102, 0x3e0293ee, v178
	v_fmamk_f32 v121, v103, 0x3e0293ee, v178
	v_fmamk_f32 v122, v100, 0x3e0293ee, v178
	v_fmamk_f32 v123, v101, 0x3e0293ee, v178
	v_fmamk_f32 v124, v98, 0x3e0293ee, v178
	v_fmamk_f32 v125, v99, 0x3e0293ee, v178
	v_mfma_f32_32x32x16_bf16 v[32:47], v[68:71], v[242:245], v[32:47]
	ds_read_b64_tr_b16 v[242:243], v209 offset:0x5600
	ds_read_b64_tr_b16 v[244:245], v209 offset:0x5e00
	v_mov_b32_e32 v96, v179
	v_exp_f32_e32 v237, v80
	v_exp_f32_e32 v239, v81
	v_exp_f32_e32 v235, v82
	v_exp_f32_e32 v238, v83
	s_waitcnt lgkmcnt(4)
	v_mfma_f32_32x32x16_bf16 v[32:47], v[72:75], v[246:249], v[32:47]
	ds_read_b64_tr_b16 v[246:247], v209 offset:0x6600
	ds_read_b64_tr_b16 v[248:249], v209 offset:0x6e00
	v_exp_f32_e32 v234, v84
	v_exp_f32_e32 v236, v85
	v_exp_f32_e32 v232, v86
	v_exp_f32_e32 v233, v87
	v_mfma_f32_32x32x16_bf16 v[32:47], v[76:79], v[250:253], v[32:47]
	ds_read_b64_tr_b16 v[250:251], v209 offset:0x7600
	ds_read_b64_tr_b16 v[252:253], v209 offset:0x7e00
	v_exp_f32_e32 v228, v88
	v_exp_f32_e32 v231, v89
	v_exp_f32_e32 v179, v90
	v_exp_f32_e32 v229, v91
	s_waitcnt lgkmcnt(4)
	v_mfma_f32_32x32x16_bf16 v[16:31], v[64:67], v[196:199], v[16:31]
	v_exp_f32_e32 v177, v92
	v_exp_f32_e32 v230, v93
	v_exp_f32_e32 v178, v94
	v_exp_f32_e32 v227, v95
	v_mfma_f32_32x32x16_bf16 v[16:31], v[68:71], v[242:245], v[16:31]
	s_waitcnt lgkmcnt(0)
	v_mfma_f32_32x32x16_bf16 v[16:31], v[72:75], v[246:249], v[16:31]
	v_mfma_f32_32x32x16_bf16 v[16:31], v[76:79], v[250:253], v[16:31]
	v_readlane_b32 s54, v255, 30
	v_readlane_b32 s55, v255, 31
	s_andn2_b64 vcc, exec, s[42:43]
	s_cbranch_vccnz .Lhs2_bar1
	s_waitcnt vmcnt(0)
	s_and_b64 vcc, exec, s[10:11]
	ds_write_b128 v208, v[164:167] offset:49152
	ds_write_b128 v208, v[172:175] offset:57344
	s_cbranch_vccnz .Lhs2_bar1
	s_mov_b32 s10, 0x667f3bcd
	v_add_f64 v[64:65], s[94:95], -v[188:189]
	s_mov_b32 s11, 0x4026a09e
	v_mul_f64 v[64:65], v[64:65], s[10:11]
	v_cvt_f32_f64_e32 v64, v[64:65]
	ds_write_b32 v221, v64 offset:256

; __device__ __forceinline__ void partialSM(f32x16& p0, f32x16& p1, float& m_reg, float& mn, float& alpha) {
;     ...
;     if (__builtin_expect(__all((pmax - m_reg) * SCALE <= THR), 1)) { mn = m_reg; alpha = 1.f; }
;     else { mn = fmaxf(m_reg, pmax); alpha = __builtin_amdgcn_exp2f((m_reg - mn) * C2); m_reg = mn; }
.Lhs1_slow:
	v_max_f32_e32 v251, v176, v176
	v_max_f32_e32 v250, v251, v250
	v_sub_f32_e32 v251, v176, v250
	v_mul_f32_e32 v251, 0x3e0293ee, v251
	v_exp_f32_e32 v226, v251
	v_mov_b32_e32 v227, v250
	s_branch .Lhs1_join
.Lhs2_slow:
	v_max_f32_e32 v177, v227, v227
	v_max_f32_e32 v176, v177, v176
	v_sub_f32_e32 v177, v227, v176
	v_mul_f32_e32 v177, 0x3e0293ee, v177
	v_exp_f32_e32 v179, v177
	s_branch .Lhs2_join
